# glr skinny GEMM hand-written: weight rows staged once via LDS into registers, activation rows fetched as full row pieces through wave-private LDS transpose, 4 steps of loads in flight
# baseline (speedup 1.0000x reference)
.LBB0_1137:
	s_cmpk_gt_i32 s97, 0xff
	v_readfirstlane_b32 s2, v0
	s_cbranch_scc1 .LBB0_1146
	s_lshr_b32 s3, s2, 6
	s_and_b32 s4, s3, 3
	s_lshr_b32 s5, s3, 2
	v_and_b32_e32 v1, 15, v0
	v_bfe_u32 v2, v0, 4, 2
	v_and_b32_e32 v3, 63, v0
	s_waitcnt lgkmcnt(0)
	s_add_u32 s0, s92, 0x4200000
	s_addc_u32 s1, s93, 0
	v_lshlrev_b32_e32 v24, 4, v0
	v_add_u32_e32 v25, 0x2000, v24
	v_add_u32_e32 v26, 0x2000, v25
	v_add_u32_e32 v27, 0x2000, v26
	v_add_u32_e32 v28, 0x2000, v27
	v_add_u32_e32 v29, 0x2000, v28
	v_add_u32_e32 v30, 0x2000, v29
	v_add_u32_e32 v31, 0x2000, v30
	global_load_dwordx4 v[40:43], v24, s[0:1]
	global_load_dwordx4 v[44:47], v25, s[0:1]
	global_load_dwordx4 v[48:51], v26, s[0:1]
	global_load_dwordx4 v[52:55], v27, s[0:1]
	global_load_dwordx4 v[56:59], v28, s[0:1]
	global_load_dwordx4 v[60:63], v29, s[0:1]
	global_load_dwordx4 v[64:67], v30, s[0:1]
	global_load_dwordx4 v[68:71], v31, s[0:1]
	v_lshrrev_b32_e32 v32, 8, v0
	v_and_b32_e32 v33, 0xff, v0
	v_mul_u32_u24_e32 v32, 0x1010, v32
	v_lshl_add_u32 v32, v33, 4, v32
	s_waitcnt vmcnt(0)
	ds_write_b128 v32, v[40:43]
	ds_write_b128 v32, v[44:47] offset:8224
	ds_write_b128 v32, v[48:51] offset:16448
	ds_write_b128 v32, v[52:55] offset:24672
	ds_write_b128 v32, v[56:59] offset:32896
	ds_write_b128 v32, v[60:63] offset:41120
	ds_write_b128 v32, v[64:67] offset:49344
	ds_write_b128 v32, v[68:71] offset:57568
	s_waitcnt lgkmcnt(0)
	s_barrier
	v_mul_u32_u24_e32 v34, 0x1010, v1
	v_lshl_add_u32 v34, v2, 4, v34
	s_lshl_b32 s6, s5, 11
	v_add_u32_e32 v34, s6, v34
	ds_read_b128 v[120:123], v34
	ds_read_b128 v[124:127], v34 offset:64
	ds_read_b128 v[128:131], v34 offset:128
	ds_read_b128 v[132:135], v34 offset:192
	ds_read_b128 v[136:139], v34 offset:256
	ds_read_b128 v[140:143], v34 offset:320
	ds_read_b128 v[144:147], v34 offset:384
	ds_read_b128 v[148:151], v34 offset:448
	ds_read_b128 v[152:155], v34 offset:512
	ds_read_b128 v[156:159], v34 offset:576
	ds_read_b128 v[160:163], v34 offset:640
	ds_read_b128 v[164:167], v34 offset:704
	ds_read_b128 v[168:171], v34 offset:768
	ds_read_b128 v[172:175], v34 offset:832
	ds_read_b128 v[176:179], v34 offset:896
	ds_read_b128 v[180:183], v34 offset:960
	ds_read_b128 v[184:187], v34 offset:1024
	ds_read_b128 v[188:191], v34 offset:1088
	ds_read_b128 v[192:195], v34 offset:1152
	ds_read_b128 v[196:199], v34 offset:1216
	ds_read_b128 v[200:203], v34 offset:1280
	ds_read_b128 v[204:207], v34 offset:1344
	ds_read_b128 v[208:211], v34 offset:1408
	ds_read_b128 v[212:215], v34 offset:1472
	ds_read_b128 v[216:219], v34 offset:1536
	ds_read_b128 v[220:223], v34 offset:1600
	ds_read_b128 v[224:227], v34 offset:1664
	ds_read_b128 v[228:231], v34 offset:1728
	ds_read_b128 v[232:235], v34 offset:1792
	ds_read_b128 v[236:239], v34 offset:1856
	ds_read_b128 v[240:243], v34 offset:1920
	ds_read_b128 v[244:247], v34 offset:1984
	s_waitcnt lgkmcnt(0)
	s_barrier
	v_lshrrev_b32_e32 v35, 4, v3
	v_and_b32_e32 v36, 15, v3
	v_lshlrev_b32_e32 v24, 12, v35
	v_lshl_add_u32 v24, v36, 4, v24
	v_add_u32_e32 v25, 0x4000, v24
	v_add_u32_e32 v26, 0x4000, v25
	v_add_u32_e32 v27, 0x4000, v26
	s_mul_i32 s6, s3, 0x2200
	v_mul_u32_u24_e32 v28, 0x110, v35
	v_lshl_add_u32 v28, v36, 4, v28
	v_add_u32_e32 v28, s6, v28
	v_mul_u32_u24_e32 v29, 0x110, v1
	v_lshl_add_u32 v29, v2, 4, v29
	v_add_u32_e32 v29, s6, v29
	v_mov_b32_e32 v30, 0x358637bd
	s_mov_b32 s12, s97
.Lglr_loop:
	s_lshl_b32 s6, s12, 18
	s_lshl_b32 s7, s4, 16
	s_add_i32 s6, s6, s7
	s_lshl_b32 s7, s5, 11
	s_add_i32 s6, s6, s7
	s_add_u32 s0, s92, 0x6400000
	s_addc_u32 s1, s93, 0
	s_add_u32 s0, s0, s6
	s_addc_u32 s1, s1, 0
	global_load_dwordx4 v[40:43], v24, s[0:1]
	global_load_dwordx4 v[44:47], v25, s[0:1]
	global_load_dwordx4 v[48:51], v26, s[0:1]
	global_load_dwordx4 v[52:55], v27, s[0:1]
	global_load_dwordx4 v[56:59], v24, s[0:1] offset:256
	global_load_dwordx4 v[60:63], v25, s[0:1] offset:256
	global_load_dwordx4 v[64:67], v26, s[0:1] offset:256
	global_load_dwordx4 v[68:71], v27, s[0:1] offset:256
	global_load_dwordx4 v[72:75], v24, s[0:1] offset:512
	global_load_dwordx4 v[76:79], v25, s[0:1] offset:512
	global_load_dwordx4 v[80:83], v26, s[0:1] offset:512
	global_load_dwordx4 v[84:87], v27, s[0:1] offset:512
	global_load_dwordx4 v[88:91], v24, s[0:1] offset:768
	global_load_dwordx4 v[92:95], v25, s[0:1] offset:768
	global_load_dwordx4 v[96:99], v26, s[0:1] offset:768
	global_load_dwordx4 v[100:103], v27, s[0:1] offset:768
	s_waitcnt vmcnt(12)
	ds_write_b128 v28, v[40:43] offset:0
	ds_write_b128 v28, v[44:47] offset:1088
	ds_write_b128 v28, v[48:51] offset:2176
	ds_write_b128 v28, v[52:55] offset:3264
	global_load_dwordx4 v[40:43], v24, s[0:1] offset:1024
	global_load_dwordx4 v[44:47], v25, s[0:1] offset:1024
	global_load_dwordx4 v[48:51], v26, s[0:1] offset:1024
	global_load_dwordx4 v[52:55], v27, s[0:1] offset:1024
	s_waitcnt lgkmcnt(0)
	ds_read_b128 v[8:11], v29 offset:0
	ds_read_b128 v[12:15], v29 offset:64
	ds_read_b128 v[16:19], v29 offset:128
	ds_read_b128 v[20:23], v29 offset:192
	s_waitcnt lgkmcnt(3)
	v_mfma_f32_16x16x32_bf16 v[4:7], v[120:123], v[8:11], 0
	s_waitcnt lgkmcnt(2)
	v_mfma_f32_16x16x32_bf16 v[4:7], v[124:127], v[12:15], v[4:7]
	s_waitcnt lgkmcnt(1)
	v_mfma_f32_16x16x32_bf16 v[4:7], v[128:131], v[16:19], v[4:7]
	s_waitcnt lgkmcnt(0)
	v_mfma_f32_16x16x32_bf16 v[4:7], v[132:135], v[20:23], v[4:7]
	s_waitcnt vmcnt(12)
	ds_write_b128 v28, v[56:59] offset:4352
	ds_write_b128 v28, v[60:63] offset:5440
	ds_write_b128 v28, v[64:67] offset:6528
	ds_write_b128 v28, v[68:71] offset:7616
	global_load_dwordx4 v[56:59], v24, s[0:1] offset:1280
	global_load_dwordx4 v[60:63], v25, s[0:1] offset:1280
	global_load_dwordx4 v[64:67], v26, s[0:1] offset:1280
	global_load_dwordx4 v[68:71], v27, s[0:1] offset:1280
	s_waitcnt lgkmcnt(0)
	ds_read_b128 v[8:11], v29 offset:4352
	ds_read_b128 v[12:15], v29 offset:4416
	ds_read_b128 v[16:19], v29 offset:4480
	ds_read_b128 v[20:23], v29 offset:4544
	s_waitcnt lgkmcnt(3)
	v_mfma_f32_16x16x32_bf16 v[4:7], v[136:139], v[8:11], v[4:7]
	s_waitcnt lgkmcnt(2)
	v_mfma_f32_16x16x32_bf16 v[4:7], v[140:143], v[12:15], v[4:7]
	s_waitcnt lgkmcnt(1)
	v_mfma_f32_16x16x32_bf16 v[4:7], v[144:147], v[16:19], v[4:7]
	s_waitcnt lgkmcnt(0)
	v_mfma_f32_16x16x32_bf16 v[4:7], v[148:151], v[20:23], v[4:7]
	s_waitcnt vmcnt(12)
	ds_write_b128 v28, v[72:75] offset:0
	ds_write_b128 v28, v[76:79] offset:1088
	ds_write_b128 v28, v[80:83] offset:2176
	ds_write_b128 v28, v[84:87] offset:3264
	global_load_dwordx4 v[72:75], v24, s[0:1] offset:1536
	global_load_dwordx4 v[76:79], v25, s[0:1] offset:1536
	global_load_dwordx4 v[80:83], v26, s[0:1] offset:1536
	global_load_dwordx4 v[84:87], v27, s[0:1] offset:1536
	s_waitcnt lgkmcnt(0)
	ds_read_b128 v[8:11], v29 offset:0
	ds_read_b128 v[12:15], v29 offset:64
	ds_read_b128 v[16:19], v29 offset:128
	ds_read_b128 v[20:23], v29 offset:192
	s_waitcnt lgkmcnt(3)
	v_mfma_f32_16x16x32_bf16 v[4:7], v[152:155], v[8:11], v[4:7]
	s_waitcnt lgkmcnt(2)
	v_mfma_f32_16x16x32_bf16 v[4:7], v[156:159], v[12:15], v[4:7]
	s_waitcnt lgkmcnt(1)
	v_mfma_f32_16x16x32_bf16 v[4:7], v[160:163], v[16:19], v[4:7]
	s_waitcnt lgkmcnt(0)
	v_mfma_f32_16x16x32_bf16 v[4:7], v[164:167], v[20:23], v[4:7]
	s_waitcnt vmcnt(12)
	ds_write_b128 v28, v[88:91] offset:4352
	ds_write_b128 v28, v[92:95] offset:5440
	ds_write_b128 v28, v[96:99] offset:6528
	ds_write_b128 v28, v[100:103] offset:7616
	global_load_dwordx4 v[88:91], v24, s[0:1] offset:1792
	global_load_dwordx4 v[92:95], v25, s[0:1] offset:1792
	global_load_dwordx4 v[96:99], v26, s[0:1] offset:1792
	global_load_dwordx4 v[100:103], v27, s[0:1] offset:1792
	s_waitcnt lgkmcnt(0)
	ds_read_b128 v[8:11], v29 offset:4352
	ds_read_b128 v[12:15], v29 offset:4416
	ds_read_b128 v[16:19], v29 offset:4480
	ds_read_b128 v[20:23], v29 offset:4544
	s_waitcnt lgkmcnt(3)
	v_mfma_f32_16x16x32_bf16 v[4:7], v[168:171], v[8:11], v[4:7]
	s_waitcnt lgkmcnt(2)
	v_mfma_f32_16x16x32_bf16 v[4:7], v[172:175], v[12:15], v[4:7]
	s_waitcnt lgkmcnt(1)
	v_mfma_f32_16x16x32_bf16 v[4:7], v[176:179], v[16:19], v[4:7]
	s_waitcnt lgkmcnt(0)
	v_mfma_f32_16x16x32_bf16 v[4:7], v[180:183], v[20:23], v[4:7]
	s_waitcnt vmcnt(12)
	ds_write_b128 v28, v[40:43] offset:0
	ds_write_b128 v28, v[44:47] offset:1088
	ds_write_b128 v28, v[48:51] offset:2176
	ds_write_b128 v28, v[52:55] offset:3264
	s_waitcnt lgkmcnt(0)
	ds_read_b128 v[8:11], v29 offset:0
	ds_read_b128 v[12:15], v29 offset:64
	ds_read_b128 v[16:19], v29 offset:128
	ds_read_b128 v[20:23], v29 offset:192
	s_waitcnt lgkmcnt(3)
	v_mfma_f32_16x16x32_bf16 v[4:7], v[184:187], v[8:11], v[4:7]
	s_waitcnt lgkmcnt(2)
	v_mfma_f32_16x16x32_bf16 v[4:7], v[188:191], v[12:15], v[4:7]
	s_waitcnt lgkmcnt(1)
	v_mfma_f32_16x16x32_bf16 v[4:7], v[192:195], v[16:19], v[4:7]
	s_waitcnt lgkmcnt(0)
	v_mfma_f32_16x16x32_bf16 v[4:7], v[196:199], v[20:23], v[4:7]
	s_waitcnt vmcnt(8)
	ds_write_b128 v28, v[56:59] offset:4352
	ds_write_b128 v28, v[60:63] offset:5440
	ds_write_b128 v28, v[64:67] offset:6528
	ds_write_b128 v28, v[68:71] offset:7616
	s_waitcnt lgkmcnt(0)
	ds_read_b128 v[8:11], v29 offset:4352
	ds_read_b128 v[12:15], v29 offset:4416
	ds_read_b128 v[16:19], v29 offset:4480
	ds_read_b128 v[20:23], v29 offset:4544
	s_waitcnt lgkmcnt(3)
	v_mfma_f32_16x16x32_bf16 v[4:7], v[200:203], v[8:11], v[4:7]
	s_waitcnt lgkmcnt(2)
	v_mfma_f32_16x16x32_bf16 v[4:7], v[204:207], v[12:15], v[4:7]
	s_waitcnt lgkmcnt(1)
	v_mfma_f32_16x16x32_bf16 v[4:7], v[208:211], v[16:19], v[4:7]
	s_waitcnt lgkmcnt(0)
	v_mfma_f32_16x16x32_bf16 v[4:7], v[212:215], v[20:23], v[4:7]
	s_waitcnt vmcnt(4)
	ds_write_b128 v28, v[72:75] offset:0
	ds_write_b128 v28, v[76:79] offset:1088
	ds_write_b128 v28, v[80:83] offset:2176
	ds_write_b128 v28, v[84:87] offset:3264
	s_waitcnt lgkmcnt(0)
	ds_read_b128 v[8:11], v29 offset:0
	ds_read_b128 v[12:15], v29 offset:64
	ds_read_b128 v[16:19], v29 offset:128
	ds_read_b128 v[20:23], v29 offset:192
	s_waitcnt lgkmcnt(3)
	v_mfma_f32_16x16x32_bf16 v[4:7], v[216:219], v[8:11], v[4:7]
	s_waitcnt lgkmcnt(2)
	v_mfma_f32_16x16x32_bf16 v[4:7], v[220:223], v[12:15], v[4:7]
	s_waitcnt lgkmcnt(1)
	v_mfma_f32_16x16x32_bf16 v[4:7], v[224:227], v[16:19], v[4:7]
	s_waitcnt lgkmcnt(0)
	v_mfma_f32_16x16x32_bf16 v[4:7], v[228:231], v[20:23], v[4:7]
	s_waitcnt vmcnt(0)
	ds_write_b128 v28, v[88:91] offset:4352
	ds_write_b128 v28, v[92:95] offset:5440
	ds_write_b128 v28, v[96:99] offset:6528
	ds_write_b128 v28, v[100:103] offset:7616
	s_waitcnt lgkmcnt(0)
	ds_read_b128 v[8:11], v29 offset:4352
	ds_read_b128 v[12:15], v29 offset:4416
	ds_read_b128 v[16:19], v29 offset:4480
	ds_read_b128 v[20:23], v29 offset:4544
	s_waitcnt lgkmcnt(3)
	v_mfma_f32_16x16x32_bf16 v[4:7], v[232:235], v[8:11], v[4:7]
	s_waitcnt lgkmcnt(2)
	v_mfma_f32_16x16x32_bf16 v[4:7], v[236:239], v[12:15], v[4:7]
	s_waitcnt lgkmcnt(1)
	v_mfma_f32_16x16x32_bf16 v[4:7], v[240:243], v[16:19], v[4:7]
	s_waitcnt lgkmcnt(0)
	v_mfma_f32_16x16x32_bf16 v[4:7], v[244:247], v[20:23], v[4:7]
	s_lshl_b32 s6, s4, 10
	v_lshl_add_u32 v31, v3, 4, s6
	v_add_u32_e32 v31, 0x11000, v31
	s_cmp_eq_u32 s5, 1
	s_cbranch_scc0 .Lglr_nowr
	s_nop 7
	s_nop 1
	ds_write_b128 v31, v[4:7]
.Lglr_nowr:
	s_waitcnt lgkmcnt(0)
	s_barrier
	s_cmp_eq_u32 s5, 0
	s_cbranch_scc0 .Lglr_nost
	ds_read_b128 v[8:11], v31
	s_lshl_b32 s6, s12, 6
	s_lshl_b32 s7, s4, 4
	s_add_i32 s6, s6, s7
	v_add_u32_e32 v12, s6, v1
	s_add_u32 s0, s92, 0x1cc40000
	s_addc_u32 s1, s93, 0
	v_lshlrev_b32_e32 v13, 2, v12
	global_load_dword v14, v13, s[0:1]
	s_add_u32 s0, s92, 0x1cc90000
	s_addc_u32 s1, s93, 0
	v_lshlrev_b32_e32 v13, 6, v12
	v_lshl_add_u32 v13, v2, 4, v13
	s_waitcnt vmcnt(0) lgkmcnt(0)
	v_fmamk_f32 v14, v14, 0x3a000000, v30
	v_rsq_f32_e32 v14, v14
	v_add_f32_e32 v4, v4, v8
	v_add_f32_e32 v5, v5, v9
	v_add_f32_e32 v6, v6, v10
	v_add_f32_e32 v7, v7, v11
	v_mul_f32_e32 v4, v4, v14
	v_mul_f32_e32 v5, v5, v14
	v_mul_f32_e32 v6, v6, v14
	v_mul_f32_e32 v7, v7, v14
	global_store_dwordx4 v13, v[4:7], s[0:1]
.Lglr_nost:
	s_add_i32 s12, s12, s96
	s_cmpk_lt_i32 s12, 0x100
	s_cbranch_scc0 .Lglr_done
	s_barrier
	s_branch .Lglr_loop
.Lglr_done:
.LBB0_1146:
	s_cmp_gt_i32 s95, 6
	s_cselect_b64 s[0:1], -1, 0
	s_and_b64 s[2:3], s[8:9], s[0:1]
	s_andn2_b64 vcc, exec, s[2:3]
	s_cbranch_vccnz .LBB0_1200
	s_waitcnt vmcnt(0)
	s_waitcnt vmcnt(0) lgkmcnt(0)
	s_barrier
	s_mov_b64 s[2:3], exec
	v_readlane_b32 s4, v255, 10
	v_readlane_b32 s5, v255, 11
	s_and_b64 s[4:5], s[2:3], s[4:5]
	s_mov_b64 exec, s[4:5]
	s_cbranch_execz .LBB0_1199
	s_add_i32 s4, 0, 0x20000
	v_mov_b32_e32 v1, s4
	s_waitcnt vmcnt(0) expcnt(0) lgkmcnt(0)
	ds_read_b32 v3, v1
	s_add_i32 s4, 0, 0x20004
	v_mov_b32_e32 v1, s4
	ds_read_b32 v1, v1
	s_waitcnt lgkmcnt(1)
	v_cmp_ne_u32_e32 vcc, 0, v3
	s_cbranch_vccnz .LBB0_1163
	v_readlane_b32 s4, v255, 8
	v_readlane_b32 s5, v255, 9
	s_load_dwordx2 s[8:9], s[4:5], 0x4
	s_add_u32 s4, s92, 0x1cf10200
	s_addc_u32 s5, s93, 0
	s_add_u32 s6, s92, 0x1cf10400
	s_addc_u32 s7, s93, 0
	s_waitcnt lgkmcnt(0)
	s_mul_i32 s33, s8, s96
	s_add_u32 s8, s92, 0x1cf10500
	s_mul_i32 s33, s33, s9
	s_addc_u32 s9, s93, 0
	s_add_u32 s10, s92, 0x1cf10600
	s_addc_u32 s11, s93, 0
	s_add_u32 s12, s92, 0x1cf10700
	s_addc_u32 s13, s93, 0
	s_add_u32 s14, s92, 0x1cf10800
	s_addc_u32 s15, s93, 0
	s_add_u32 s16, s92, 0x1cf10900
	s_addc_u32 s17, s93, 0
	s_add_u32 s18, s92, 0x1cf10a00
	s_addc_u32 s19, s93, 0
	s_add_u32 s20, s92, 0x1cf10b00
	s_addc_u32 s21, s93, 0
	s_add_u32 s22, s92, 0x1cf10c00
	s_addc_u32 s23, s93, 0
	s_add_u32 s24, s92, 0x1cf10d00
	s_addc_u32 s25, s93, 0
	s_add_u32 s26, s92, 0x1cf10e00
	s_addc_u32 s27, s93, 0
	s_add_u32 s28, s92, 0x1cf10f00
	s_addc_u32 s29, s93, 0
	s_add_u32 s30, s92, 0x1cf11000
	s_addc_u32 s31, s93, 0
	s_add_u32 s34, s92, 0x1cf11100
	s_addc_u32 s35, s93, 0
	s_add_u32 s36, s92, 0x1cf11200
	s_addc_u32 s37, s93, 0
	s_add_u32 s38, s92, 0x1cf11300
	s_addc_u32 s39, s93, 0
	s_mov_b32 s46, 1
	v_mov_b32_e32 v17, 0
	s_branch .LBB0_1151
